# G1/G3/G4/G5: first K iteration peeled with C=0 on each accumulator's first MFMA, 128 per-tile zeroing v_movs dropped
# speedup vs baseline: 1.0297x; 1.0077x over previous
.LBB0_53:
	v_lshl_add_u32 v171, s48, 8, v241
	v_lshlrev_b32_e32 v171, 2, v171
	global_load_dword v164, v171, s[70:71]
	global_load_dword v165, v171, s[70:71] offset:64
	global_load_dword v166, v171, s[70:71] offset:128
	global_load_dword v167, v171, s[70:71] offset:192
	global_load_dword v246, v171, s[70:71] offset:512
	global_load_dword v247, v171, s[70:71] offset:576
	global_load_dword v248, v171, s[70:71] offset:640
	global_load_dword v249, v171, s[70:71] offset:704
	s_add_u32 s0, s4, 0x40080
	s_addc_u32 s1, s5, 0
	s_add_u32 s3, s20, 0x100
	s_addc_u32 s20, s21, 0
	s_mov_b32 s21, -2
	s_add_u32 s4, s0, 0xfffc0080
	s_addc_u32 s5, s1, -1
	s_add_i32 s36, 0, 0x10000
	v_add_u32_e32 v2, s36, v243
	ds_read_b128 v[132:135], v2
	ds_read_b128 v[136:139], v2 offset:1024
	ds_read_b128 v[140:143], v2 offset:2048
	ds_read_b128 v[144:147], v2 offset:3072
	s_cmp_eq_u32 s21, 12
	s_cselect_b32 s17, s51, s5
	s_cselect_b32 s16, s50, s4
	s_cselect_b32 s5, s7, s20
	s_cselect_b32 s4, s6, s3
	v_lshl_add_u64 v[168:169], s[0:1], 0, v[184:185]
	s_add_i32 m0, s23, 0xc000
	ds_read_b128 v[148:151], v245
	ds_read_b128 v[152:155], v245 offset:1024
	ds_read_b128 v[156:159], v245 offset:2048
	ds_read_b128 v[160:163], v245 offset:3072
	ds_read_b128 v[188:191], v245 offset:4096
	ds_read_b128 v[192:195], v245 offset:5120
	ds_read_b128 v[196:199], v245 offset:6144
	ds_read_b128 v[200:203], v245 offset:7168
	global_load_lds_dwordx4 v[168:169], off
	v_lshl_add_u64 v[168:169], s[0:1], 0, v[186:187]
	s_add_i32 m0, s23, 0xe000
	s_nop 0
	global_load_lds_dwordx4 v[168:169], off
	s_waitcnt lgkmcnt(8)
	s_barrier
	s_waitcnt lgkmcnt(0)
	s_waitcnt lgkmcnt(0)
	v_mfma_f32_16x16x32_bf16 v[128:131], v[132:135], v[148:151], 0
	v_mfma_f32_16x16x32_bf16 v[124:127], v[140:143], v[148:151], 0
	v_mfma_f32_16x16x32_bf16 v[120:123], v[132:135], v[156:159], 0
	v_mfma_f32_16x16x32_bf16 v[116:119], v[140:143], v[156:159], 0
	v_mfma_f32_16x16x32_bf16 v[112:115], v[132:135], v[188:191], 0
	v_mfma_f32_16x16x32_bf16 v[108:111], v[140:143], v[188:191], 0
	v_mfma_f32_16x16x32_bf16 v[104:107], v[132:135], v[196:199], 0
	v_mfma_f32_16x16x32_bf16 v[100:103], v[140:143], v[196:199], 0
	v_mfma_f32_16x16x32_bf16 v[128:131], v[136:139], v[152:155], v[128:131]
	v_mfma_f32_16x16x32_bf16 v[124:127], v[144:147], v[152:155], v[124:127]
	v_mfma_f32_16x16x32_bf16 v[120:123], v[136:139], v[160:163], v[120:123]
	v_mfma_f32_16x16x32_bf16 v[116:119], v[144:147], v[160:163], v[116:119]
	v_mfma_f32_16x16x32_bf16 v[112:115], v[136:139], v[192:195], v[112:115]
	v_mfma_f32_16x16x32_bf16 v[108:111], v[144:147], v[192:195], v[108:111]
	v_mfma_f32_16x16x32_bf16 v[104:107], v[136:139], v[200:203], v[104:107]
	v_mfma_f32_16x16x32_bf16 v[100:103], v[144:147], v[200:203], v[100:103]
	s_barrier
	s_add_i32 s40, 0, 0x14000
	s_add_i32 s36, s36, s18
	v_add_u32_e32 v2, s40, v243
	v_lshl_add_u64 v[168:169], s[4:5], 0, v[172:173]
	s_mov_b32 m0, s36
	ds_read_b128 v[204:207], v2
	ds_read_b128 v[208:211], v2 offset:1024
	ds_read_b128 v[234:237], v2 offset:2048
	ds_read_b128 v[220:223], v2 offset:3072
	global_load_lds_dwordx4 v[168:169], off
	v_lshl_add_u64 v[238:239], s[4:5], 0, v[176:177]
	s_add_i32 m0, s36, 0x2000
	s_nop 0
	global_load_lds_dwordx4 v[238:239], off
	s_barrier
	s_waitcnt lgkmcnt(0)
	s_waitcnt lgkmcnt(0)
	v_mfma_f32_16x16x32_bf16 v[64:67], v[204:207], v[148:151], 0
	v_mfma_f32_16x16x32_bf16 v[60:63], v[234:237], v[148:151], 0
	v_mfma_f32_16x16x32_bf16 v[56:59], v[204:207], v[156:159], 0
	v_mfma_f32_16x16x32_bf16 v[52:55], v[234:237], v[156:159], 0
	v_mfma_f32_16x16x32_bf16 v[48:51], v[204:207], v[188:191], 0
	v_mfma_f32_16x16x32_bf16 v[44:47], v[234:237], v[188:191], 0
	v_mfma_f32_16x16x32_bf16 v[40:43], v[204:207], v[196:199], 0
	v_mfma_f32_16x16x32_bf16 v[36:39], v[234:237], v[196:199], 0
	v_mfma_f32_16x16x32_bf16 v[64:67], v[208:211], v[152:155], v[64:67]
	v_mfma_f32_16x16x32_bf16 v[60:63], v[220:223], v[152:155], v[60:63]
	v_mfma_f32_16x16x32_bf16 v[56:59], v[208:211], v[160:163], v[56:59]
	v_mfma_f32_16x16x32_bf16 v[52:55], v[220:223], v[160:163], v[52:55]
	v_mfma_f32_16x16x32_bf16 v[48:51], v[208:211], v[192:195], v[48:51]
	v_mfma_f32_16x16x32_bf16 v[44:47], v[220:223], v[192:195], v[44:47]
	v_mfma_f32_16x16x32_bf16 v[40:43], v[208:211], v[200:203], v[40:43]
	v_mfma_f32_16x16x32_bf16 v[36:39], v[220:223], v[200:203], v[36:39]
	s_mov_b32 m0, s23
	v_lshl_add_u64 v[214:215], s[16:17], 0, v[0:1]
	s_barrier
	ds_read_b128 v[148:151], v245 offset:16384
	ds_read_b128 v[152:155], v245 offset:17408
	ds_read_b128 v[156:159], v245 offset:18432
	ds_read_b128 v[160:163], v245 offset:19456
	ds_read_b128 v[188:191], v245 offset:20480
	ds_read_b128 v[192:195], v245 offset:21504
	ds_read_b128 v[196:199], v245 offset:22528
	ds_read_b128 v[200:203], v245 offset:23552
	global_load_lds_dwordx4 v[214:215], off
	v_lshl_add_u64 v[224:225], s[16:17], 0, v[174:175]
	s_mov_b32 m0, s26
	s_nop 0
	global_load_lds_dwordx4 v[224:225], off
	s_barrier
	s_waitcnt lgkmcnt(0)
	s_waitcnt lgkmcnt(0)
	v_mfma_f32_16x16x32_bf16 v[96:99], v[132:135], v[148:151], 0
	v_mfma_f32_16x16x32_bf16 v[92:95], v[140:143], v[148:151], 0
	v_mfma_f32_16x16x32_bf16 v[88:91], v[132:135], v[156:159], 0
	v_mfma_f32_16x16x32_bf16 v[84:87], v[140:143], v[156:159], 0
	v_mfma_f32_16x16x32_bf16 v[80:83], v[132:135], v[188:191], 0
	v_mfma_f32_16x16x32_bf16 v[76:79], v[140:143], v[188:191], 0
	v_mfma_f32_16x16x32_bf16 v[72:75], v[132:135], v[196:199], 0
	v_mfma_f32_16x16x32_bf16 v[68:71], v[140:143], v[196:199], 0
	v_mfma_f32_16x16x32_bf16 v[96:99], v[136:139], v[152:155], v[96:99]
	v_mfma_f32_16x16x32_bf16 v[92:95], v[144:147], v[152:155], v[92:95]
	v_mfma_f32_16x16x32_bf16 v[88:91], v[136:139], v[160:163], v[88:91]
	v_mfma_f32_16x16x32_bf16 v[84:87], v[144:147], v[160:163], v[84:87]
	v_mfma_f32_16x16x32_bf16 v[80:83], v[136:139], v[192:195], v[80:83]
	v_mfma_f32_16x16x32_bf16 v[76:79], v[144:147], v[192:195], v[76:79]
	v_mfma_f32_16x16x32_bf16 v[72:75], v[136:139], v[200:203], v[72:75]
	v_mfma_f32_16x16x32_bf16 v[68:71], v[144:147], v[200:203], v[68:71]
	s_barrier
	s_add_u32 s36, s4, 0x40000
	s_addc_u32 s37, s5, 0
	s_add_i32 s40, s40, s18
	v_lshl_add_u64 v[132:133], s[36:37], 0, v[172:173]
	s_mov_b32 m0, s40
	s_nop 0
	global_load_lds_dwordx4 v[132:133], off
	v_lshl_add_u64 v[132:133], s[36:37], 0, v[176:177]
	s_add_i32 m0, s40, 0x2000
	s_nop 0
	global_load_lds_dwordx4 v[132:133], off
	s_waitcnt vmcnt(6)
	s_barrier
	v_mfma_f32_16x16x32_bf16 v[32:35], v[204:207], v[148:151], 0
	v_mfma_f32_16x16x32_bf16 v[28:31], v[234:237], v[148:151], 0
	v_mfma_f32_16x16x32_bf16 v[24:27], v[204:207], v[156:159], 0
	v_mfma_f32_16x16x32_bf16 v[20:23], v[234:237], v[156:159], 0
	v_mfma_f32_16x16x32_bf16 v[16:19], v[204:207], v[188:191], 0
	v_mfma_f32_16x16x32_bf16 v[12:15], v[234:237], v[188:191], 0
	v_mfma_f32_16x16x32_bf16 v[8:11], v[204:207], v[196:199], 0
	v_mfma_f32_16x16x32_bf16 v[4:7], v[234:237], v[196:199], 0
	v_mfma_f32_16x16x32_bf16 v[32:35], v[208:211], v[152:155], v[32:35]
	v_mfma_f32_16x16x32_bf16 v[28:31], v[220:223], v[152:155], v[28:31]
	v_mfma_f32_16x16x32_bf16 v[24:27], v[208:211], v[160:163], v[24:27]
	v_mfma_f32_16x16x32_bf16 v[20:23], v[220:223], v[160:163], v[20:23]
	v_mfma_f32_16x16x32_bf16 v[16:19], v[208:211], v[192:195], v[16:19]
	v_mfma_f32_16x16x32_bf16 v[12:15], v[220:223], v[192:195], v[12:15]
	v_mfma_f32_16x16x32_bf16 v[8:11], v[208:211], v[200:203], v[8:11]
	v_mfma_f32_16x16x32_bf16 v[4:7], v[220:223], v[200:203], v[4:7]
	s_add_i32 s36, 0, 0x18000
	v_add_u32_e32 v2, s36, v243
	s_barrier
	ds_read_b128 v[132:135], v2
	ds_read_b128 v[136:139], v2 offset:1024
	ds_read_b128 v[140:143], v2 offset:2048
	ds_read_b128 v[144:147], v2 offset:3072
	s_add_u32 s16, s16, 0x40000
	s_addc_u32 s17, s17, 0
	s_mov_b32 m0, s27
	v_lshl_add_u64 v[204:205], s[16:17], 0, v[0:1]
	ds_read_b128 v[148:151], v245 offset:32768
	ds_read_b128 v[152:155], v245 offset:33792
	ds_read_b128 v[156:159], v245 offset:34816
	ds_read_b128 v[160:163], v245 offset:35840
	ds_read_b128 v[188:191], v245 offset:36864
	ds_read_b128 v[192:195], v245 offset:37888
	ds_read_b128 v[196:199], v245 offset:38912
	ds_read_b128 v[200:203], v245 offset:39936
	global_load_lds_dwordx4 v[204:205], off
	v_lshl_add_u64 v[204:205], s[16:17], 0, v[174:175]
	s_mov_b32 m0, s30
	s_nop 0
	global_load_lds_dwordx4 v[204:205], off
	s_waitcnt lgkmcnt(8)
	s_barrier
	s_waitcnt lgkmcnt(0)
	s_waitcnt lgkmcnt(0)
	v_mfma_f32_16x16x32_bf16 v[128:131], v[132:135], v[148:151], v[128:131]
	v_mfma_f32_16x16x32_bf16 v[124:127], v[140:143], v[148:151], v[124:127]
	v_mfma_f32_16x16x32_bf16 v[120:123], v[132:135], v[156:159], v[120:123]
	v_mfma_f32_16x16x32_bf16 v[116:119], v[140:143], v[156:159], v[116:119]
	v_mfma_f32_16x16x32_bf16 v[112:115], v[132:135], v[188:191], v[112:115]
	v_mfma_f32_16x16x32_bf16 v[108:111], v[140:143], v[188:191], v[108:111]
	v_mfma_f32_16x16x32_bf16 v[104:107], v[132:135], v[196:199], v[104:107]
	v_mfma_f32_16x16x32_bf16 v[100:103], v[140:143], v[196:199], v[100:103]
	v_mfma_f32_16x16x32_bf16 v[128:131], v[136:139], v[152:155], v[128:131]
	v_mfma_f32_16x16x32_bf16 v[124:127], v[144:147], v[152:155], v[124:127]
	v_mfma_f32_16x16x32_bf16 v[120:123], v[136:139], v[160:163], v[120:123]
	v_mfma_f32_16x16x32_bf16 v[116:119], v[144:147], v[160:163], v[116:119]
	v_mfma_f32_16x16x32_bf16 v[112:115], v[136:139], v[192:195], v[112:115]
	v_mfma_f32_16x16x32_bf16 v[108:111], v[144:147], v[192:195], v[108:111]
	v_mfma_f32_16x16x32_bf16 v[104:107], v[136:139], v[200:203], v[104:107]
	v_mfma_f32_16x16x32_bf16 v[100:103], v[144:147], v[200:203], v[100:103]
	s_barrier
	s_add_i32 s16, 0, 0x1c000
	s_add_i32 s17, s36, s18
	v_add_u32_e32 v2, s16, v243
	v_lshl_add_u64 v[168:169], v[168:169], 0, s[28:29]
	s_mov_b32 m0, s17
	ds_read_b128 v[204:207], v2
	ds_read_b128 v[208:211], v2 offset:1024
	ds_read_b128 v[220:223], v2 offset:2048
	ds_read_b128 v[234:237], v2 offset:3072
	global_load_lds_dwordx4 v[168:169], off
	v_lshl_add_u64 v[168:169], v[238:239], 0, s[28:29]
	s_add_i32 m0, s17, 0x2000
	s_nop 0
	global_load_lds_dwordx4 v[168:169], off
	s_barrier
	s_waitcnt lgkmcnt(0)
	s_waitcnt lgkmcnt(0)
	v_mfma_f32_16x16x32_bf16 v[64:67], v[204:207], v[148:151], v[64:67]
	v_mfma_f32_16x16x32_bf16 v[60:63], v[220:223], v[148:151], v[60:63]
	v_mfma_f32_16x16x32_bf16 v[56:59], v[204:207], v[156:159], v[56:59]
	v_mfma_f32_16x16x32_bf16 v[52:55], v[220:223], v[156:159], v[52:55]
	v_mfma_f32_16x16x32_bf16 v[48:51], v[204:207], v[188:191], v[48:51]
	v_mfma_f32_16x16x32_bf16 v[44:47], v[220:223], v[188:191], v[44:47]
	v_mfma_f32_16x16x32_bf16 v[40:43], v[204:207], v[196:199], v[40:43]
	v_mfma_f32_16x16x32_bf16 v[36:39], v[220:223], v[196:199], v[36:39]
	v_mfma_f32_16x16x32_bf16 v[64:67], v[208:211], v[152:155], v[64:67]
	v_mfma_f32_16x16x32_bf16 v[60:63], v[234:237], v[152:155], v[60:63]
	v_mfma_f32_16x16x32_bf16 v[56:59], v[208:211], v[160:163], v[56:59]
	v_mfma_f32_16x16x32_bf16 v[52:55], v[234:237], v[160:163], v[52:55]
	v_mfma_f32_16x16x32_bf16 v[48:51], v[208:211], v[192:195], v[48:51]
	v_mfma_f32_16x16x32_bf16 v[44:47], v[234:237], v[192:195], v[44:47]
	v_mfma_f32_16x16x32_bf16 v[40:43], v[208:211], v[200:203], v[40:43]
	v_mfma_f32_16x16x32_bf16 v[36:39], v[234:237], v[200:203], v[36:39]
	s_mov_b32 m0, s76
	v_lshl_add_u64 v[168:169], v[214:215], 0, s[28:29]
	s_barrier
	ds_read_b128 v[148:151], v245 offset:49152
	ds_read_b128 v[152:155], v245 offset:50176
	ds_read_b128 v[156:159], v245 offset:51200
	ds_read_b128 v[160:163], v245 offset:52224
	ds_read_b128 v[188:191], v245 offset:53248
	ds_read_b128 v[192:195], v245 offset:54272
	ds_read_b128 v[196:199], v245 offset:55296
	ds_read_b128 v[200:203], v245 offset:56320
	global_load_lds_dwordx4 v[168:169], off
	v_lshl_add_u64 v[168:169], v[224:225], 0, s[28:29]
	s_mov_b32 m0, s77
	s_nop 0
	global_load_lds_dwordx4 v[168:169], off
	s_barrier
	s_waitcnt lgkmcnt(0)
	s_waitcnt lgkmcnt(0)
	v_mfma_f32_16x16x32_bf16 v[96:99], v[132:135], v[148:151], v[96:99]
	v_mfma_f32_16x16x32_bf16 v[92:95], v[140:143], v[148:151], v[92:95]
	v_mfma_f32_16x16x32_bf16 v[88:91], v[132:135], v[156:159], v[88:91]
	v_mfma_f32_16x16x32_bf16 v[84:87], v[140:143], v[156:159], v[84:87]
	v_mfma_f32_16x16x32_bf16 v[80:83], v[132:135], v[188:191], v[80:83]
	v_mfma_f32_16x16x32_bf16 v[76:79], v[140:143], v[188:191], v[76:79]
	v_mfma_f32_16x16x32_bf16 v[72:75], v[132:135], v[196:199], v[72:75]
	v_mfma_f32_16x16x32_bf16 v[68:71], v[140:143], v[196:199], v[68:71]
	v_mfma_f32_16x16x32_bf16 v[96:99], v[136:139], v[152:155], v[96:99]
	v_mfma_f32_16x16x32_bf16 v[92:95], v[144:147], v[152:155], v[92:95]
	v_mfma_f32_16x16x32_bf16 v[88:91], v[136:139], v[160:163], v[88:91]
	v_mfma_f32_16x16x32_bf16 v[84:87], v[144:147], v[160:163], v[84:87]
	v_mfma_f32_16x16x32_bf16 v[80:83], v[136:139], v[192:195], v[80:83]
	v_mfma_f32_16x16x32_bf16 v[76:79], v[144:147], v[192:195], v[76:79]
	v_mfma_f32_16x16x32_bf16 v[72:75], v[136:139], v[200:203], v[72:75]
	v_mfma_f32_16x16x32_bf16 v[68:71], v[144:147], v[200:203], v[68:71]
	s_barrier
	s_add_u32 s4, s4, 0x40080
	s_addc_u32 s5, s5, 0
	s_add_i32 s16, s16, s18
	v_lshl_add_u64 v[132:133], s[4:5], 0, v[172:173]
	s_mov_b32 m0, s16
	s_nop 0
	global_load_lds_dwordx4 v[132:133], off
	v_lshl_add_u64 v[132:133], s[4:5], 0, v[176:177]
	s_add_i32 m0, s16, 0x2000
	s_nop 0
	global_load_lds_dwordx4 v[132:133], off
	s_waitcnt vmcnt(6)
	s_barrier
	v_mfma_f32_16x16x32_bf16 v[32:35], v[204:207], v[148:151], v[32:35]
	v_mfma_f32_16x16x32_bf16 v[28:31], v[220:223], v[148:151], v[28:31]
	v_mfma_f32_16x16x32_bf16 v[24:27], v[204:207], v[156:159], v[24:27]
	v_mfma_f32_16x16x32_bf16 v[20:23], v[220:223], v[156:159], v[20:23]
	v_mfma_f32_16x16x32_bf16 v[16:19], v[204:207], v[188:191], v[16:19]
	v_mfma_f32_16x16x32_bf16 v[12:15], v[220:223], v[188:191], v[12:15]
	v_mfma_f32_16x16x32_bf16 v[8:11], v[204:207], v[196:199], v[8:11]
	v_mfma_f32_16x16x32_bf16 v[4:7], v[220:223], v[196:199], v[4:7]
	v_mfma_f32_16x16x32_bf16 v[32:35], v[208:211], v[152:155], v[32:35]
	v_mfma_f32_16x16x32_bf16 v[28:31], v[234:237], v[152:155], v[28:31]
	v_mfma_f32_16x16x32_bf16 v[24:27], v[208:211], v[160:163], v[24:27]
	v_mfma_f32_16x16x32_bf16 v[20:23], v[234:237], v[160:163], v[20:23]
	v_mfma_f32_16x16x32_bf16 v[16:19], v[208:211], v[192:195], v[16:19]
	v_mfma_f32_16x16x32_bf16 v[12:15], v[234:237], v[192:195], v[12:15]
	v_mfma_f32_16x16x32_bf16 v[8:11], v[208:211], v[200:203], v[8:11]
	v_mfma_f32_16x16x32_bf16 v[4:7], v[234:237], v[200:203], v[4:7]
	s_add_i32 s21, s21, 2
	s_add_u32 s0, s0, 0x100
	s_addc_u32 s1, s1, 0
	s_add_u32 s3, s3, 0x100
	s_addc_u32 s20, s20, 0
	s_cmp_gt_u32 s21, 13
	s_barrier

.LBB0_839:
	s_add_u32 s10, s10, 0x40080
	s_addc_u32 s11, s11, 0
	s_add_u32 s1, s16, 0x100
	s_addc_u32 s3, s17, 0
	s_mov_b32 s44, -2
	s_add_u32 s16, s10, 0xfffc0080
	s_addc_u32 s17, s11, -1
	s_add_i32 s45, 0, 0x10000
	v_add_u32_e32 v147, s45, v141
	ds_read_b128 v[148:151], v147
	ds_read_b128 v[152:155], v147 offset:1024
	ds_read_b128 v[156:159], v147 offset:2048
	ds_read_b128 v[160:163], v147 offset:3072
	s_cmp_eq_u32 s44, 12
	s_cselect_b32 s17, s5, s17
	s_cselect_b32 s16, s4, s16
	s_cselect_b32 s21, s9, s3
	s_cselect_b32 s20, s8, s1
	v_lshl_add_u64 v[168:169], s[10:11], 0, v[136:137]
	s_add_i32 m0, s23, 0xc000
	ds_read_b128 v[172:175], v146
	ds_read_b128 v[176:179], v146 offset:1024
	ds_read_b128 v[180:183], v146 offset:2048
	ds_read_b128 v[184:187], v146 offset:3072
	ds_read_b128 v[188:191], v146 offset:4096
	ds_read_b128 v[192:195], v146 offset:5120
	ds_read_b128 v[196:199], v146 offset:6144
	ds_read_b128 v[200:203], v146 offset:7168
	global_load_lds_dwordx4 v[168:169], off
	v_lshl_add_u64 v[168:169], s[10:11], 0, v[138:139]
	s_add_i32 m0, s23, 0xe000
	s_nop 0
	global_load_lds_dwordx4 v[168:169], off
	s_waitcnt lgkmcnt(8)
	s_barrier
	s_waitcnt lgkmcnt(0)
	s_waitcnt lgkmcnt(0)
	v_mfma_f32_16x16x32_bf16 v[128:131], v[148:151], v[172:175], 0
	v_mfma_f32_16x16x32_bf16 v[124:127], v[156:159], v[172:175], 0
	v_mfma_f32_16x16x32_bf16 v[120:123], v[148:151], v[180:183], 0
	v_mfma_f32_16x16x32_bf16 v[116:119], v[156:159], v[180:183], 0
	v_mfma_f32_16x16x32_bf16 v[112:115], v[148:151], v[188:191], 0
	v_mfma_f32_16x16x32_bf16 v[108:111], v[156:159], v[188:191], 0
	v_mfma_f32_16x16x32_bf16 v[104:107], v[148:151], v[196:199], 0
	v_mfma_f32_16x16x32_bf16 v[100:103], v[156:159], v[196:199], 0
	v_mfma_f32_16x16x32_bf16 v[128:131], v[152:155], v[176:179], v[128:131]
	v_mfma_f32_16x16x32_bf16 v[124:127], v[160:163], v[176:179], v[124:127]
	v_mfma_f32_16x16x32_bf16 v[120:123], v[152:155], v[184:187], v[120:123]
	v_mfma_f32_16x16x32_bf16 v[116:119], v[160:163], v[184:187], v[116:119]
	v_mfma_f32_16x16x32_bf16 v[112:115], v[152:155], v[192:195], v[112:115]
	v_mfma_f32_16x16x32_bf16 v[108:111], v[160:163], v[192:195], v[108:111]
	v_mfma_f32_16x16x32_bf16 v[104:107], v[152:155], v[200:203], v[104:107]
	v_mfma_f32_16x16x32_bf16 v[100:103], v[160:163], v[200:203], v[100:103]
	s_barrier
	s_add_i32 s50, 0, 0x14000
	s_add_i32 s45, s45, s22
	v_add_u32_e32 v147, s50, v141
	v_lshl_add_u64 v[168:169], s[20:21], 0, v[2:3]
	s_mov_b32 m0, s45
	ds_read_b128 v[204:207], v147
	ds_read_b128 v[208:211], v147 offset:1024
	ds_read_b128 v[220:223], v147 offset:2048
	ds_read_b128 v[234:237], v147 offset:3072
	global_load_lds_dwordx4 v[168:169], off
	v_lshl_add_u64 v[214:215], s[20:21], 0, v[0:1]
	s_add_i32 m0, s45, 0x2000
	s_nop 0
	global_load_lds_dwordx4 v[214:215], off
	s_barrier
	s_waitcnt lgkmcnt(0)
	s_waitcnt lgkmcnt(0)
	v_mfma_f32_16x16x32_bf16 v[84:87], v[204:207], v[172:175], 0
	v_mfma_f32_16x16x32_bf16 v[76:79], v[220:223], v[172:175], 0
	v_mfma_f32_16x16x32_bf16 v[72:75], v[204:207], v[180:183], 0
	v_mfma_f32_16x16x32_bf16 v[68:71], v[220:223], v[180:183], 0
	v_mfma_f32_16x16x32_bf16 v[56:59], v[204:207], v[188:191], 0
	v_mfma_f32_16x16x32_bf16 v[52:55], v[220:223], v[188:191], 0
	v_mfma_f32_16x16x32_bf16 v[44:47], v[204:207], v[196:199], 0
	v_mfma_f32_16x16x32_bf16 v[36:39], v[220:223], v[196:199], 0
	v_mfma_f32_16x16x32_bf16 v[84:87], v[208:211], v[176:179], v[84:87]
	v_mfma_f32_16x16x32_bf16 v[76:79], v[234:237], v[176:179], v[76:79]
	v_mfma_f32_16x16x32_bf16 v[72:75], v[208:211], v[184:187], v[72:75]
	v_mfma_f32_16x16x32_bf16 v[68:71], v[234:237], v[184:187], v[68:71]
	v_mfma_f32_16x16x32_bf16 v[56:59], v[208:211], v[192:195], v[56:59]
	v_mfma_f32_16x16x32_bf16 v[52:55], v[234:237], v[192:195], v[52:55]
	v_mfma_f32_16x16x32_bf16 v[44:47], v[208:211], v[200:203], v[44:47]
	v_mfma_f32_16x16x32_bf16 v[36:39], v[234:237], v[200:203], v[36:39]
	s_mov_b32 m0, s23
	v_lshl_add_u64 v[224:225], s[16:17], 0, v[134:135]
	s_barrier
	ds_read_b128 v[172:175], v146 offset:16384
	ds_read_b128 v[176:179], v146 offset:17408
	ds_read_b128 v[180:183], v146 offset:18432
	ds_read_b128 v[184:187], v146 offset:19456
	ds_read_b128 v[188:191], v146 offset:20480
	ds_read_b128 v[192:195], v146 offset:21504
	ds_read_b128 v[196:199], v146 offset:22528
	ds_read_b128 v[200:203], v146 offset:23552
	global_load_lds_dwordx4 v[224:225], off
	v_lshl_add_u64 v[238:239], s[16:17], 0, v[132:133]
	s_mov_b32 m0, s26
	s_nop 0
	global_load_lds_dwordx4 v[238:239], off
	s_barrier
	s_waitcnt lgkmcnt(0)
	s_waitcnt lgkmcnt(0)
	v_mfma_f32_16x16x32_bf16 v[96:99], v[148:151], v[172:175], 0
	v_mfma_f32_16x16x32_bf16 v[92:95], v[156:159], v[172:175], 0
	v_mfma_f32_16x16x32_bf16 v[88:91], v[148:151], v[180:183], 0
	v_mfma_f32_16x16x32_bf16 v[80:83], v[156:159], v[180:183], 0
	v_mfma_f32_16x16x32_bf16 v[64:67], v[148:151], v[188:191], 0
	v_mfma_f32_16x16x32_bf16 v[60:63], v[156:159], v[188:191], 0
	v_mfma_f32_16x16x32_bf16 v[48:51], v[148:151], v[196:199], 0
	v_mfma_f32_16x16x32_bf16 v[40:43], v[156:159], v[196:199], 0
	v_mfma_f32_16x16x32_bf16 v[96:99], v[152:155], v[176:179], v[96:99]
	v_mfma_f32_16x16x32_bf16 v[92:95], v[160:163], v[176:179], v[92:95]
	v_mfma_f32_16x16x32_bf16 v[88:91], v[152:155], v[184:187], v[88:91]
	v_mfma_f32_16x16x32_bf16 v[80:83], v[160:163], v[184:187], v[80:83]
	v_mfma_f32_16x16x32_bf16 v[64:67], v[152:155], v[192:195], v[64:67]
	v_mfma_f32_16x16x32_bf16 v[60:63], v[160:163], v[192:195], v[60:63]
	v_mfma_f32_16x16x32_bf16 v[48:51], v[152:155], v[200:203], v[48:51]
	v_mfma_f32_16x16x32_bf16 v[40:43], v[160:163], v[200:203], v[40:43]
	s_barrier
	s_add_u32 s48, s20, 0x40000
	s_addc_u32 s49, s21, 0
	s_add_i32 s45, s50, s22
	v_lshl_add_u64 v[148:149], s[48:49], 0, v[2:3]
	s_mov_b32 m0, s45
	s_nop 0
	global_load_lds_dwordx4 v[148:149], off
	v_lshl_add_u64 v[148:149], s[48:49], 0, v[0:1]
	s_add_i32 m0, s45, 0x2000
	s_nop 0
	global_load_lds_dwordx4 v[148:149], off
	s_waitcnt vmcnt(6)
	s_barrier
	v_mfma_f32_16x16x32_bf16 v[32:35], v[204:207], v[172:175], 0
	v_mfma_f32_16x16x32_bf16 v[28:31], v[220:223], v[172:175], 0
	v_mfma_f32_16x16x32_bf16 v[24:27], v[204:207], v[180:183], 0
	v_mfma_f32_16x16x32_bf16 v[20:23], v[220:223], v[180:183], 0
	v_mfma_f32_16x16x32_bf16 v[16:19], v[204:207], v[188:191], 0
	v_mfma_f32_16x16x32_bf16 v[12:15], v[220:223], v[188:191], 0
	v_mfma_f32_16x16x32_bf16 v[8:11], v[204:207], v[196:199], 0
	v_mfma_f32_16x16x32_bf16 v[4:7], v[220:223], v[196:199], 0
	v_mfma_f32_16x16x32_bf16 v[32:35], v[208:211], v[176:179], v[32:35]
	v_mfma_f32_16x16x32_bf16 v[28:31], v[234:237], v[176:179], v[28:31]
	v_mfma_f32_16x16x32_bf16 v[24:27], v[208:211], v[184:187], v[24:27]
	v_mfma_f32_16x16x32_bf16 v[20:23], v[234:237], v[184:187], v[20:23]
	v_mfma_f32_16x16x32_bf16 v[16:19], v[208:211], v[192:195], v[16:19]
	v_mfma_f32_16x16x32_bf16 v[12:15], v[234:237], v[192:195], v[12:15]
	v_mfma_f32_16x16x32_bf16 v[8:11], v[208:211], v[200:203], v[8:11]
	v_mfma_f32_16x16x32_bf16 v[4:7], v[234:237], v[200:203], v[4:7]
	s_add_i32 s45, 0, 0x18000
	v_add_u32_e32 v147, s45, v141
	s_barrier
	ds_read_b128 v[148:151], v147
	ds_read_b128 v[152:155], v147 offset:1024
	ds_read_b128 v[156:159], v147 offset:2048
	ds_read_b128 v[160:163], v147 offset:3072
	s_add_u32 s16, s16, 0x40000
	s_addc_u32 s17, s17, 0
	s_mov_b32 m0, s27
	v_lshl_add_u64 v[204:205], s[16:17], 0, v[134:135]
	ds_read_b128 v[172:175], v146 offset:32768
	ds_read_b128 v[176:179], v146 offset:33792
	ds_read_b128 v[180:183], v146 offset:34816
	ds_read_b128 v[184:187], v146 offset:35840
	ds_read_b128 v[188:191], v146 offset:36864
	ds_read_b128 v[192:195], v146 offset:37888
	ds_read_b128 v[196:199], v146 offset:38912
	ds_read_b128 v[200:203], v146 offset:39936
	global_load_lds_dwordx4 v[204:205], off
	v_lshl_add_u64 v[204:205], s[16:17], 0, v[132:133]
	s_mov_b32 m0, s30
	s_nop 0
	global_load_lds_dwordx4 v[204:205], off
	s_waitcnt lgkmcnt(8)
	s_barrier
	s_waitcnt lgkmcnt(0)
	s_waitcnt lgkmcnt(0)
	v_mfma_f32_16x16x32_bf16 v[128:131], v[148:151], v[172:175], v[128:131]
	v_mfma_f32_16x16x32_bf16 v[124:127], v[156:159], v[172:175], v[124:127]
	v_mfma_f32_16x16x32_bf16 v[120:123], v[148:151], v[180:183], v[120:123]
	v_mfma_f32_16x16x32_bf16 v[116:119], v[156:159], v[180:183], v[116:119]
	v_mfma_f32_16x16x32_bf16 v[112:115], v[148:151], v[188:191], v[112:115]
	v_mfma_f32_16x16x32_bf16 v[108:111], v[156:159], v[188:191], v[108:111]
	v_mfma_f32_16x16x32_bf16 v[104:107], v[148:151], v[196:199], v[104:107]
	v_mfma_f32_16x16x32_bf16 v[100:103], v[156:159], v[196:199], v[100:103]
	v_mfma_f32_16x16x32_bf16 v[128:131], v[152:155], v[176:179], v[128:131]
	v_mfma_f32_16x16x32_bf16 v[124:127], v[160:163], v[176:179], v[124:127]
	v_mfma_f32_16x16x32_bf16 v[120:123], v[152:155], v[184:187], v[120:123]
	v_mfma_f32_16x16x32_bf16 v[116:119], v[160:163], v[184:187], v[116:119]
	v_mfma_f32_16x16x32_bf16 v[112:115], v[152:155], v[192:195], v[112:115]
	v_mfma_f32_16x16x32_bf16 v[108:111], v[160:163], v[192:195], v[108:111]
	v_mfma_f32_16x16x32_bf16 v[104:107], v[152:155], v[200:203], v[104:107]
	v_mfma_f32_16x16x32_bf16 v[100:103], v[160:163], v[200:203], v[100:103]
	s_barrier
	s_add_i32 s48, 0, 0x1c000
	s_add_i32 s16, s45, s22
	v_add_u32_e32 v147, s48, v141
	v_lshl_add_u64 v[168:169], v[168:169], 0, s[28:29]
	s_mov_b32 m0, s16
	ds_read_b128 v[204:207], v147
	ds_read_b128 v[208:211], v147 offset:1024
	ds_read_b128 v[220:223], v147 offset:2048
	ds_read_b128 v[234:237], v147 offset:3072
	global_load_lds_dwordx4 v[168:169], off
	v_lshl_add_u64 v[168:169], v[214:215], 0, s[28:29]
	s_add_i32 m0, s16, 0x2000
	s_nop 0
	global_load_lds_dwordx4 v[168:169], off
	s_barrier
	s_waitcnt lgkmcnt(0)
	s_waitcnt lgkmcnt(0)
	v_mfma_f32_16x16x32_bf16 v[84:87], v[204:207], v[172:175], v[84:87]
	v_mfma_f32_16x16x32_bf16 v[76:79], v[220:223], v[172:175], v[76:79]
	v_mfma_f32_16x16x32_bf16 v[72:75], v[204:207], v[180:183], v[72:75]
	v_mfma_f32_16x16x32_bf16 v[68:71], v[220:223], v[180:183], v[68:71]
	v_mfma_f32_16x16x32_bf16 v[56:59], v[204:207], v[188:191], v[56:59]
	v_mfma_f32_16x16x32_bf16 v[52:55], v[220:223], v[188:191], v[52:55]
	v_mfma_f32_16x16x32_bf16 v[44:47], v[204:207], v[196:199], v[44:47]
	v_mfma_f32_16x16x32_bf16 v[36:39], v[220:223], v[196:199], v[36:39]
	v_mfma_f32_16x16x32_bf16 v[84:87], v[208:211], v[176:179], v[84:87]
	v_mfma_f32_16x16x32_bf16 v[76:79], v[234:237], v[176:179], v[76:79]
	v_mfma_f32_16x16x32_bf16 v[72:75], v[208:211], v[184:187], v[72:75]
	v_mfma_f32_16x16x32_bf16 v[68:71], v[234:237], v[184:187], v[68:71]
	v_mfma_f32_16x16x32_bf16 v[56:59], v[208:211], v[192:195], v[56:59]
	v_mfma_f32_16x16x32_bf16 v[52:55], v[234:237], v[192:195], v[52:55]
	v_mfma_f32_16x16x32_bf16 v[44:47], v[208:211], v[200:203], v[44:47]
	v_mfma_f32_16x16x32_bf16 v[36:39], v[234:237], v[200:203], v[36:39]
	s_mov_b32 m0, s31
	v_lshl_add_u64 v[168:169], v[224:225], 0, s[28:29]
	s_barrier
	ds_read_b128 v[172:175], v146 offset:49152
	ds_read_b128 v[176:179], v146 offset:50176
	ds_read_b128 v[180:183], v146 offset:51200
	ds_read_b128 v[184:187], v146 offset:52224
	ds_read_b128 v[188:191], v146 offset:53248
	ds_read_b128 v[192:195], v146 offset:54272
	ds_read_b128 v[196:199], v146 offset:55296
	ds_read_b128 v[200:203], v146 offset:56320
	global_load_lds_dwordx4 v[168:169], off
	v_lshl_add_u64 v[168:169], v[238:239], 0, s[28:29]
	s_mov_b32 m0, s36
	s_nop 0
	global_load_lds_dwordx4 v[168:169], off
	s_barrier
	s_waitcnt lgkmcnt(0)
	s_waitcnt lgkmcnt(0)
	v_mfma_f32_16x16x32_bf16 v[96:99], v[148:151], v[172:175], v[96:99]
	v_mfma_f32_16x16x32_bf16 v[92:95], v[156:159], v[172:175], v[92:95]
	v_mfma_f32_16x16x32_bf16 v[88:91], v[148:151], v[180:183], v[88:91]
	v_mfma_f32_16x16x32_bf16 v[80:83], v[156:159], v[180:183], v[80:83]
	v_mfma_f32_16x16x32_bf16 v[64:67], v[148:151], v[188:191], v[64:67]
	v_mfma_f32_16x16x32_bf16 v[60:63], v[156:159], v[188:191], v[60:63]
	v_mfma_f32_16x16x32_bf16 v[48:51], v[148:151], v[196:199], v[48:51]
	v_mfma_f32_16x16x32_bf16 v[40:43], v[156:159], v[196:199], v[40:43]
	v_mfma_f32_16x16x32_bf16 v[96:99], v[152:155], v[176:179], v[96:99]
	v_mfma_f32_16x16x32_bf16 v[92:95], v[160:163], v[176:179], v[92:95]
	v_mfma_f32_16x16x32_bf16 v[88:91], v[152:155], v[184:187], v[88:91]
	v_mfma_f32_16x16x32_bf16 v[80:83], v[160:163], v[184:187], v[80:83]
	v_mfma_f32_16x16x32_bf16 v[64:67], v[152:155], v[192:195], v[64:67]
	v_mfma_f32_16x16x32_bf16 v[60:63], v[160:163], v[192:195], v[60:63]
	v_mfma_f32_16x16x32_bf16 v[48:51], v[152:155], v[200:203], v[48:51]
	v_mfma_f32_16x16x32_bf16 v[40:43], v[160:163], v[200:203], v[40:43]
	s_barrier
	s_add_u32 s16, s20, 0x40080
	s_addc_u32 s17, s21, 0
	s_add_i32 s20, s48, s22
	v_lshl_add_u64 v[148:149], s[16:17], 0, v[2:3]
	s_mov_b32 m0, s20
	s_nop 0
	global_load_lds_dwordx4 v[148:149], off
	v_lshl_add_u64 v[148:149], s[16:17], 0, v[0:1]
	s_add_i32 m0, s20, 0x2000
	s_nop 0
	global_load_lds_dwordx4 v[148:149], off
	s_waitcnt vmcnt(6)
	s_barrier
	v_mfma_f32_16x16x32_bf16 v[32:35], v[204:207], v[172:175], v[32:35]
	v_mfma_f32_16x16x32_bf16 v[28:31], v[220:223], v[172:175], v[28:31]
	v_mfma_f32_16x16x32_bf16 v[24:27], v[204:207], v[180:183], v[24:27]
	v_mfma_f32_16x16x32_bf16 v[20:23], v[220:223], v[180:183], v[20:23]
	v_mfma_f32_16x16x32_bf16 v[16:19], v[204:207], v[188:191], v[16:19]
	v_mfma_f32_16x16x32_bf16 v[12:15], v[220:223], v[188:191], v[12:15]
	v_mfma_f32_16x16x32_bf16 v[8:11], v[204:207], v[196:199], v[8:11]
	v_mfma_f32_16x16x32_bf16 v[4:7], v[220:223], v[196:199], v[4:7]
	v_mfma_f32_16x16x32_bf16 v[32:35], v[208:211], v[176:179], v[32:35]
	v_mfma_f32_16x16x32_bf16 v[28:31], v[234:237], v[176:179], v[28:31]
	v_mfma_f32_16x16x32_bf16 v[24:27], v[208:211], v[184:187], v[24:27]
	v_mfma_f32_16x16x32_bf16 v[20:23], v[234:237], v[184:187], v[20:23]
	v_mfma_f32_16x16x32_bf16 v[16:19], v[208:211], v[192:195], v[16:19]
	v_mfma_f32_16x16x32_bf16 v[12:15], v[234:237], v[192:195], v[12:15]
	v_mfma_f32_16x16x32_bf16 v[8:11], v[208:211], v[200:203], v[8:11]
	v_mfma_f32_16x16x32_bf16 v[4:7], v[234:237], v[200:203], v[4:7]
	s_add_i32 s44, s44, 2
	s_add_u32 s10, s10, 0x100
	s_addc_u32 s11, s11, 0
	s_add_u32 s1, s1, 0x100
	s_addc_u32 s3, s3, 0
	s_cmp_gt_u32 s44, 13
	s_barrier

.LBB0_1097:
	s_add_u32 s2, s2, 0x40080
	s_addc_u32 s3, s3, 0
	s_add_u32 s9, s4, 0x100
	s_addc_u32 s11, s5, 0
	s_mov_b32 s53, -2
	v_lshl_add_u32 v171, s37, 8, v156
	v_lshlrev_b32_e32 v171, 2, v171
	global_load_dword v164, v171, s[70:71]
	global_load_dword v165, v171, s[70:71] offset:64
	global_load_dword v166, v171, s[70:71] offset:128
	global_load_dword v167, v171, s[70:71] offset:192
	global_load_dword v246, v171, s[70:71] offset:512
	global_load_dword v247, v171, s[70:71] offset:576
	global_load_dword v248, v171, s[70:71] offset:640
	global_load_dword v249, v171, s[70:71] offset:704
	s_add_u32 s4, s2, 0xfffc0080
	s_addc_u32 s5, s3, -1
	s_add_i32 s72, 0, 0x10000
	v_add_u32_e32 v152, s72, v157
	ds_read_b128 v[140:143], v152
	ds_read_b128 v[144:147], v152 offset:1024
	ds_read_b128 v[148:151], v152 offset:2048
	ds_read_b128 v[152:155], v152 offset:3072
	s_cmp_eq_u32 s53, 12
	s_cselect_b32 s17, s49, s5
	s_cselect_b32 s16, s48, s4
	s_cselect_b32 s5, s21, s11
	s_cselect_b32 s4, s20, s9
	v_lshl_add_u64 v[168:169], s[2:3], 0, v[136:137]
	s_add_i32 m0, s26, 0xc000
	ds_read_b128 v[160:163], v159
	ds_read_b128 v[172:175], v159 offset:1024
	ds_read_b128 v[176:179], v159 offset:2048
	ds_read_b128 v[180:183], v159 offset:3072
	ds_read_b128 v[184:187], v159 offset:4096
	ds_read_b128 v[188:191], v159 offset:5120
	ds_read_b128 v[192:195], v159 offset:6144
	ds_read_b128 v[196:199], v159 offset:7168
	global_load_lds_dwordx4 v[168:169], off
	v_lshl_add_u64 v[168:169], s[2:3], 0, v[138:139]
	s_add_i32 m0, s26, 0xe000
	s_nop 0
	global_load_lds_dwordx4 v[168:169], off
	s_waitcnt lgkmcnt(8)
	s_barrier
	s_waitcnt lgkmcnt(0)
	s_waitcnt lgkmcnt(0)
	v_mfma_f32_16x16x32_bf16 v[128:131], v[140:143], v[160:163], 0
	v_mfma_f32_16x16x32_bf16 v[124:127], v[148:151], v[160:163], 0
	v_mfma_f32_16x16x32_bf16 v[120:123], v[140:143], v[176:179], 0
	v_mfma_f32_16x16x32_bf16 v[116:119], v[148:151], v[176:179], 0
	v_mfma_f32_16x16x32_bf16 v[112:115], v[140:143], v[184:187], 0
	v_mfma_f32_16x16x32_bf16 v[108:111], v[148:151], v[184:187], 0
	v_mfma_f32_16x16x32_bf16 v[104:107], v[140:143], v[192:195], 0
	v_mfma_f32_16x16x32_bf16 v[100:103], v[148:151], v[192:195], 0
	v_mfma_f32_16x16x32_bf16 v[128:131], v[144:147], v[172:175], v[128:131]
	v_mfma_f32_16x16x32_bf16 v[124:127], v[152:155], v[172:175], v[124:127]
	v_mfma_f32_16x16x32_bf16 v[120:123], v[144:147], v[180:183], v[120:123]
	v_mfma_f32_16x16x32_bf16 v[116:119], v[152:155], v[180:183], v[116:119]
	v_mfma_f32_16x16x32_bf16 v[112:115], v[144:147], v[188:191], v[112:115]
	v_mfma_f32_16x16x32_bf16 v[108:111], v[152:155], v[188:191], v[108:111]
	v_mfma_f32_16x16x32_bf16 v[104:107], v[144:147], v[196:199], v[104:107]
	v_mfma_f32_16x16x32_bf16 v[100:103], v[152:155], v[196:199], v[100:103]
	s_barrier
	s_add_i32 s74, 0, 0x14000
	v_add_u32_e32 v168, s74, v157
	s_add_i32 s72, s72, s23
	ds_read_b128 v[200:203], v168
	ds_read_b128 v[204:207], v168 offset:1024
	ds_read_b128 v[208:211], v168 offset:2048
	ds_read_b128 v[220:223], v168 offset:3072
	v_lshl_add_u64 v[168:169], s[4:5], 0, v[2:3]
	s_mov_b32 m0, s72
	v_lshl_add_u64 v[214:215], s[4:5], 0, v[0:1]
	global_load_lds_dwordx4 v[168:169], off
	s_add_i32 m0, s72, 0x2000
	s_nop 0
	global_load_lds_dwordx4 v[214:215], off
	s_barrier
	s_waitcnt lgkmcnt(0)
	s_waitcnt lgkmcnt(0)
	v_mfma_f32_16x16x32_bf16 v[72:75], v[200:203], v[160:163], 0
	v_mfma_f32_16x16x32_bf16 v[68:71], v[208:211], v[160:163], 0
	v_mfma_f32_16x16x32_bf16 v[56:59], v[200:203], v[176:179], 0
	v_mfma_f32_16x16x32_bf16 v[52:55], v[208:211], v[176:179], 0
	v_mfma_f32_16x16x32_bf16 v[48:51], v[200:203], v[184:187], 0
	v_mfma_f32_16x16x32_bf16 v[44:47], v[208:211], v[184:187], 0
	v_mfma_f32_16x16x32_bf16 v[40:43], v[200:203], v[192:195], 0
	v_mfma_f32_16x16x32_bf16 v[36:39], v[208:211], v[192:195], 0
	v_mfma_f32_16x16x32_bf16 v[72:75], v[204:207], v[172:175], v[72:75]
	v_mfma_f32_16x16x32_bf16 v[68:71], v[220:223], v[172:175], v[68:71]
	v_mfma_f32_16x16x32_bf16 v[56:59], v[204:207], v[180:183], v[56:59]
	v_mfma_f32_16x16x32_bf16 v[52:55], v[220:223], v[180:183], v[52:55]
	v_mfma_f32_16x16x32_bf16 v[48:51], v[204:207], v[188:191], v[48:51]
	v_mfma_f32_16x16x32_bf16 v[44:47], v[220:223], v[188:191], v[44:47]
	v_mfma_f32_16x16x32_bf16 v[40:43], v[204:207], v[196:199], v[40:43]
	v_mfma_f32_16x16x32_bf16 v[36:39], v[220:223], v[196:199], v[36:39]
	s_mov_b32 m0, s26
	v_lshl_add_u64 v[224:225], s[16:17], 0, v[134:135]
	s_barrier
	ds_read_b128 v[160:163], v159 offset:16384
	ds_read_b128 v[172:175], v159 offset:17408
	ds_read_b128 v[176:179], v159 offset:18432
	ds_read_b128 v[180:183], v159 offset:19456
	ds_read_b128 v[184:187], v159 offset:20480
	ds_read_b128 v[188:191], v159 offset:21504
	ds_read_b128 v[192:195], v159 offset:22528
	ds_read_b128 v[196:199], v159 offset:23552
	global_load_lds_dwordx4 v[224:225], off
	v_lshl_add_u64 v[234:235], s[16:17], 0, v[132:133]
	s_mov_b32 m0, s27
	s_nop 0
	global_load_lds_dwordx4 v[234:235], off
	s_barrier
	s_waitcnt lgkmcnt(0)
	s_waitcnt lgkmcnt(0)
	v_mfma_f32_16x16x32_bf16 v[96:99], v[140:143], v[160:163], 0
	v_mfma_f32_16x16x32_bf16 v[92:95], v[148:151], v[160:163], 0
	v_mfma_f32_16x16x32_bf16 v[88:91], v[140:143], v[176:179], 0
	v_mfma_f32_16x16x32_bf16 v[84:87], v[148:151], v[176:179], 0
	v_mfma_f32_16x16x32_bf16 v[80:83], v[140:143], v[184:187], 0
	v_mfma_f32_16x16x32_bf16 v[76:79], v[148:151], v[184:187], 0
	v_mfma_f32_16x16x32_bf16 v[64:67], v[140:143], v[192:195], 0
	v_mfma_f32_16x16x32_bf16 v[60:63], v[148:151], v[192:195], 0
	v_mfma_f32_16x16x32_bf16 v[96:99], v[144:147], v[172:175], v[96:99]
	v_mfma_f32_16x16x32_bf16 v[92:95], v[152:155], v[172:175], v[92:95]
	v_mfma_f32_16x16x32_bf16 v[88:91], v[144:147], v[180:183], v[88:91]
	v_mfma_f32_16x16x32_bf16 v[84:87], v[152:155], v[180:183], v[84:87]
	v_mfma_f32_16x16x32_bf16 v[80:83], v[144:147], v[188:191], v[80:83]
	v_mfma_f32_16x16x32_bf16 v[76:79], v[152:155], v[188:191], v[76:79]
	v_mfma_f32_16x16x32_bf16 v[64:67], v[144:147], v[196:199], v[64:67]
	v_mfma_f32_16x16x32_bf16 v[60:63], v[152:155], v[196:199], v[60:63]
	s_barrier
	s_add_u32 s72, s4, 0x40000
	s_addc_u32 s73, s5, 0
	s_add_i32 s74, s74, s23
	v_lshl_add_u64 v[140:141], s[72:73], 0, v[2:3]
	s_mov_b32 m0, s74
	s_nop 0
	global_load_lds_dwordx4 v[140:141], off
	v_lshl_add_u64 v[140:141], s[72:73], 0, v[0:1]
	s_add_i32 m0, s74, 0x2000
	s_nop 0
	global_load_lds_dwordx4 v[140:141], off
	s_waitcnt vmcnt(6)
	s_barrier
	v_mfma_f32_16x16x32_bf16 v[32:35], v[200:203], v[160:163], 0
	v_mfma_f32_16x16x32_bf16 v[28:31], v[208:211], v[160:163], 0
	v_mfma_f32_16x16x32_bf16 v[24:27], v[200:203], v[176:179], 0
	v_mfma_f32_16x16x32_bf16 v[20:23], v[208:211], v[176:179], 0
	v_mfma_f32_16x16x32_bf16 v[16:19], v[200:203], v[184:187], 0
	v_mfma_f32_16x16x32_bf16 v[12:15], v[208:211], v[184:187], 0
	v_mfma_f32_16x16x32_bf16 v[8:11], v[200:203], v[192:195], 0
	v_mfma_f32_16x16x32_bf16 v[4:7], v[208:211], v[192:195], 0
	v_mfma_f32_16x16x32_bf16 v[32:35], v[204:207], v[172:175], v[32:35]
	v_mfma_f32_16x16x32_bf16 v[28:31], v[220:223], v[172:175], v[28:31]
	v_mfma_f32_16x16x32_bf16 v[24:27], v[204:207], v[180:183], v[24:27]
	v_mfma_f32_16x16x32_bf16 v[20:23], v[220:223], v[180:183], v[20:23]
	v_mfma_f32_16x16x32_bf16 v[16:19], v[204:207], v[188:191], v[16:19]
	v_mfma_f32_16x16x32_bf16 v[12:15], v[220:223], v[188:191], v[12:15]
	v_mfma_f32_16x16x32_bf16 v[8:11], v[204:207], v[196:199], v[8:11]
	v_mfma_f32_16x16x32_bf16 v[4:7], v[220:223], v[196:199], v[4:7]
	s_add_i32 s72, 0, 0x18000
	v_add_u32_e32 v152, s72, v157
	s_barrier
	ds_read_b128 v[140:143], v152
	ds_read_b128 v[144:147], v152 offset:1024
	ds_read_b128 v[148:151], v152 offset:2048
	ds_read_b128 v[152:155], v152 offset:3072
	s_add_u32 s16, s16, 0x40000
	s_addc_u32 s17, s17, 0
	s_mov_b32 m0, s30
	v_lshl_add_u64 v[200:201], s[16:17], 0, v[134:135]
	ds_read_b128 v[160:163], v159 offset:32768
	ds_read_b128 v[172:175], v159 offset:33792
	ds_read_b128 v[176:179], v159 offset:34816
	ds_read_b128 v[180:183], v159 offset:35840
	ds_read_b128 v[184:187], v159 offset:36864
	ds_read_b128 v[188:191], v159 offset:37888
	ds_read_b128 v[192:195], v159 offset:38912
	ds_read_b128 v[196:199], v159 offset:39936
	global_load_lds_dwordx4 v[200:201], off
	v_lshl_add_u64 v[200:201], s[16:17], 0, v[132:133]
	s_mov_b32 m0, s31
	s_nop 0
	global_load_lds_dwordx4 v[200:201], off
	s_waitcnt lgkmcnt(8)
	s_barrier
	s_waitcnt lgkmcnt(0)
	s_waitcnt lgkmcnt(0)
	v_mfma_f32_16x16x32_bf16 v[128:131], v[140:143], v[160:163], v[128:131]
	v_mfma_f32_16x16x32_bf16 v[124:127], v[148:151], v[160:163], v[124:127]
	v_mfma_f32_16x16x32_bf16 v[120:123], v[140:143], v[176:179], v[120:123]
	v_mfma_f32_16x16x32_bf16 v[116:119], v[148:151], v[176:179], v[116:119]
	v_mfma_f32_16x16x32_bf16 v[112:115], v[140:143], v[184:187], v[112:115]
	v_mfma_f32_16x16x32_bf16 v[108:111], v[148:151], v[184:187], v[108:111]
	v_mfma_f32_16x16x32_bf16 v[104:107], v[140:143], v[192:195], v[104:107]
	v_mfma_f32_16x16x32_bf16 v[100:103], v[148:151], v[192:195], v[100:103]
	v_mfma_f32_16x16x32_bf16 v[128:131], v[144:147], v[172:175], v[128:131]
	v_mfma_f32_16x16x32_bf16 v[124:127], v[152:155], v[172:175], v[124:127]
	v_mfma_f32_16x16x32_bf16 v[120:123], v[144:147], v[180:183], v[120:123]
	v_mfma_f32_16x16x32_bf16 v[116:119], v[152:155], v[180:183], v[116:119]
	v_mfma_f32_16x16x32_bf16 v[112:115], v[144:147], v[188:191], v[112:115]
	v_mfma_f32_16x16x32_bf16 v[108:111], v[152:155], v[188:191], v[108:111]
	v_mfma_f32_16x16x32_bf16 v[104:107], v[144:147], v[196:199], v[104:107]
	v_mfma_f32_16x16x32_bf16 v[100:103], v[152:155], v[196:199], v[100:103]
	s_barrier
	s_add_i32 s16, 0, 0x1c000
	s_add_i32 s17, s72, s23
	v_add_u32_e32 v170, s16, v157
	v_lshl_add_u64 v[168:169], v[168:169], 0, s[28:29]
	s_mov_b32 m0, s17
	ds_read_b128 v[200:203], v170
	ds_read_b128 v[204:207], v170 offset:1024
	ds_read_b128 v[208:211], v170 offset:2048
	ds_read_b128 v[220:223], v170 offset:3072
	global_load_lds_dwordx4 v[168:169], off
	v_lshl_add_u64 v[168:169], v[214:215], 0, s[28:29]
	s_add_i32 m0, s17, 0x2000
	s_nop 0
	global_load_lds_dwordx4 v[168:169], off
	s_barrier
	s_waitcnt lgkmcnt(0)
	s_waitcnt lgkmcnt(0)
	v_mfma_f32_16x16x32_bf16 v[72:75], v[200:203], v[160:163], v[72:75]
	v_mfma_f32_16x16x32_bf16 v[68:71], v[208:211], v[160:163], v[68:71]
	v_mfma_f32_16x16x32_bf16 v[56:59], v[200:203], v[176:179], v[56:59]
	v_mfma_f32_16x16x32_bf16 v[52:55], v[208:211], v[176:179], v[52:55]
	v_mfma_f32_16x16x32_bf16 v[48:51], v[200:203], v[184:187], v[48:51]
	v_mfma_f32_16x16x32_bf16 v[44:47], v[208:211], v[184:187], v[44:47]
	v_mfma_f32_16x16x32_bf16 v[40:43], v[200:203], v[192:195], v[40:43]
	v_mfma_f32_16x16x32_bf16 v[36:39], v[208:211], v[192:195], v[36:39]
	v_mfma_f32_16x16x32_bf16 v[72:75], v[204:207], v[172:175], v[72:75]
	v_mfma_f32_16x16x32_bf16 v[68:71], v[220:223], v[172:175], v[68:71]
	v_mfma_f32_16x16x32_bf16 v[56:59], v[204:207], v[180:183], v[56:59]
	v_mfma_f32_16x16x32_bf16 v[52:55], v[220:223], v[180:183], v[52:55]
	v_mfma_f32_16x16x32_bf16 v[48:51], v[204:207], v[188:191], v[48:51]
	v_mfma_f32_16x16x32_bf16 v[44:47], v[220:223], v[188:191], v[44:47]
	v_mfma_f32_16x16x32_bf16 v[40:43], v[204:207], v[196:199], v[40:43]
	v_mfma_f32_16x16x32_bf16 v[36:39], v[220:223], v[196:199], v[36:39]
	s_mov_b32 m0, s50
	v_lshl_add_u64 v[168:169], v[224:225], 0, s[28:29]
	s_barrier
	ds_read_b128 v[160:163], v159 offset:49152
	ds_read_b128 v[172:175], v159 offset:50176
	ds_read_b128 v[176:179], v159 offset:51200
	ds_read_b128 v[180:183], v159 offset:52224
	ds_read_b128 v[184:187], v159 offset:53248
	ds_read_b128 v[188:191], v159 offset:54272
	ds_read_b128 v[192:195], v159 offset:55296
	ds_read_b128 v[196:199], v159 offset:56320
	global_load_lds_dwordx4 v[168:169], off
	v_lshl_add_u64 v[168:169], v[234:235], 0, s[28:29]
	s_mov_b32 m0, s51
	s_nop 0
	global_load_lds_dwordx4 v[168:169], off
	s_barrier
	s_waitcnt lgkmcnt(0)
	s_waitcnt lgkmcnt(0)
	v_mfma_f32_16x16x32_bf16 v[96:99], v[140:143], v[160:163], v[96:99]
	v_mfma_f32_16x16x32_bf16 v[92:95], v[148:151], v[160:163], v[92:95]
	v_mfma_f32_16x16x32_bf16 v[88:91], v[140:143], v[176:179], v[88:91]
	v_mfma_f32_16x16x32_bf16 v[84:87], v[148:151], v[176:179], v[84:87]
	v_mfma_f32_16x16x32_bf16 v[80:83], v[140:143], v[184:187], v[80:83]
	v_mfma_f32_16x16x32_bf16 v[76:79], v[148:151], v[184:187], v[76:79]
	v_mfma_f32_16x16x32_bf16 v[64:67], v[140:143], v[192:195], v[64:67]
	v_mfma_f32_16x16x32_bf16 v[60:63], v[148:151], v[192:195], v[60:63]
	v_mfma_f32_16x16x32_bf16 v[96:99], v[144:147], v[172:175], v[96:99]
	v_mfma_f32_16x16x32_bf16 v[92:95], v[152:155], v[172:175], v[92:95]
	v_mfma_f32_16x16x32_bf16 v[88:91], v[144:147], v[180:183], v[88:91]
	v_mfma_f32_16x16x32_bf16 v[84:87], v[152:155], v[180:183], v[84:87]
	v_mfma_f32_16x16x32_bf16 v[80:83], v[144:147], v[188:191], v[80:83]
	v_mfma_f32_16x16x32_bf16 v[76:79], v[152:155], v[188:191], v[76:79]
	v_mfma_f32_16x16x32_bf16 v[64:67], v[144:147], v[196:199], v[64:67]
	v_mfma_f32_16x16x32_bf16 v[60:63], v[152:155], v[196:199], v[60:63]
	s_barrier
	s_add_u32 s4, s4, 0x40080
	s_addc_u32 s5, s5, 0
	s_add_i32 s16, s16, s23
	v_lshl_add_u64 v[140:141], s[4:5], 0, v[2:3]
	s_mov_b32 m0, s16
	s_nop 0
	global_load_lds_dwordx4 v[140:141], off
	v_lshl_add_u64 v[140:141], s[4:5], 0, v[0:1]
	s_add_i32 m0, s16, 0x2000
	s_nop 0
	global_load_lds_dwordx4 v[140:141], off
	s_waitcnt vmcnt(6)
	s_barrier
	v_mfma_f32_16x16x32_bf16 v[32:35], v[200:203], v[160:163], v[32:35]
	v_mfma_f32_16x16x32_bf16 v[28:31], v[208:211], v[160:163], v[28:31]
	v_mfma_f32_16x16x32_bf16 v[24:27], v[200:203], v[176:179], v[24:27]
	v_mfma_f32_16x16x32_bf16 v[20:23], v[208:211], v[176:179], v[20:23]
	v_mfma_f32_16x16x32_bf16 v[16:19], v[200:203], v[184:187], v[16:19]
	v_mfma_f32_16x16x32_bf16 v[12:15], v[208:211], v[184:187], v[12:15]
	v_mfma_f32_16x16x32_bf16 v[8:11], v[200:203], v[192:195], v[8:11]
	v_mfma_f32_16x16x32_bf16 v[4:7], v[208:211], v[192:195], v[4:7]
	v_mfma_f32_16x16x32_bf16 v[32:35], v[204:207], v[172:175], v[32:35]
	v_mfma_f32_16x16x32_bf16 v[28:31], v[220:223], v[172:175], v[28:31]
	v_mfma_f32_16x16x32_bf16 v[24:27], v[204:207], v[180:183], v[24:27]
	v_mfma_f32_16x16x32_bf16 v[20:23], v[220:223], v[180:183], v[20:23]
	v_mfma_f32_16x16x32_bf16 v[16:19], v[204:207], v[188:191], v[16:19]
	v_mfma_f32_16x16x32_bf16 v[12:15], v[220:223], v[188:191], v[12:15]
	v_mfma_f32_16x16x32_bf16 v[8:11], v[204:207], v[196:199], v[8:11]
	v_mfma_f32_16x16x32_bf16 v[4:7], v[220:223], v[196:199], v[4:7]
	s_add_i32 s53, s53, 2
	s_add_u32 s2, s2, 0x100
	s_addc_u32 s3, s3, 0
	s_add_u32 s9, s9, 0x100
	s_addc_u32 s11, s11, 0
	s_cmp_gt_u32 s53, 13
	s_barrier

.LBB0_1174:
	s_add_u32 s20, s20, 0x100080
	s_addc_u32 s21, s21, 0
	s_add_u32 s3, s16, 0x100
	s_addc_u32 s5, s17, 0
	s_mov_b32 s48, -2
	s_add_u32 s16, s20, 0xfff00080
	s_addc_u32 s17, s21, -1
	s_add_i32 s49, 0, 0x10000
	v_add_u32_e32 v147, s49, v141
	ds_read_b128 v[148:151], v147
	ds_read_b128 v[152:155], v147 offset:1024
	ds_read_b128 v[156:159], v147 offset:2048
	ds_read_b128 v[160:163], v147 offset:3072
	s_cmp_eq_u32 s48, 60
	s_cselect_b32 s17, s9, s17
	s_cselect_b32 s16, s8, s16
	s_cselect_b32 s23, s11, s5
	s_cselect_b32 s22, s10, s3
	v_lshl_add_u64 v[168:169], s[20:21], 0, v[136:137]
	s_add_i32 m0, s30, 0xc000
	ds_read_b128 v[172:175], v146
	ds_read_b128 v[176:179], v146 offset:1024
	ds_read_b128 v[180:183], v146 offset:2048
	ds_read_b128 v[184:187], v146 offset:3072
	ds_read_b128 v[188:191], v146 offset:4096
	ds_read_b128 v[192:195], v146 offset:5120
	ds_read_b128 v[196:199], v146 offset:6144
	ds_read_b128 v[200:203], v146 offset:7168
	global_load_lds_dwordx4 v[168:169], off
	v_lshl_add_u64 v[168:169], s[20:21], 0, v[138:139]
	s_add_i32 m0, s30, 0xe000
	s_nop 0
	global_load_lds_dwordx4 v[168:169], off
	s_waitcnt lgkmcnt(8)
	s_barrier
	s_waitcnt lgkmcnt(0)
	s_waitcnt lgkmcnt(0)
	v_mfma_f32_16x16x32_bf16 v[128:131], v[148:151], v[172:175], 0
	v_mfma_f32_16x16x32_bf16 v[124:127], v[156:159], v[172:175], 0
	v_mfma_f32_16x16x32_bf16 v[120:123], v[148:151], v[180:183], 0
	v_mfma_f32_16x16x32_bf16 v[116:119], v[156:159], v[180:183], 0
	v_mfma_f32_16x16x32_bf16 v[112:115], v[148:151], v[188:191], 0
	v_mfma_f32_16x16x32_bf16 v[108:111], v[156:159], v[188:191], 0
	v_mfma_f32_16x16x32_bf16 v[104:107], v[148:151], v[196:199], 0
	v_mfma_f32_16x16x32_bf16 v[100:103], v[156:159], v[196:199], 0
	v_mfma_f32_16x16x32_bf16 v[128:131], v[152:155], v[176:179], v[128:131]
	v_mfma_f32_16x16x32_bf16 v[124:127], v[160:163], v[176:179], v[124:127]
	v_mfma_f32_16x16x32_bf16 v[120:123], v[152:155], v[184:187], v[120:123]
	v_mfma_f32_16x16x32_bf16 v[116:119], v[160:163], v[184:187], v[116:119]
	v_mfma_f32_16x16x32_bf16 v[112:115], v[152:155], v[192:195], v[112:115]
	v_mfma_f32_16x16x32_bf16 v[108:111], v[160:163], v[192:195], v[108:111]
	v_mfma_f32_16x16x32_bf16 v[104:107], v[152:155], v[200:203], v[104:107]
	v_mfma_f32_16x16x32_bf16 v[100:103], v[160:163], v[200:203], v[100:103]
	s_barrier
	s_add_i32 s73, 0, 0x14000
	s_add_i32 s49, s49, s27
	v_add_u32_e32 v147, s73, v141
	v_lshl_add_u64 v[168:169], s[22:23], 0, v[2:3]
	s_mov_b32 m0, s49
	ds_read_b128 v[204:207], v147
	ds_read_b128 v[208:211], v147 offset:1024
	ds_read_b128 v[220:223], v147 offset:2048
	ds_read_b128 v[234:237], v147 offset:3072
	global_load_lds_dwordx4 v[168:169], off
	v_lshl_add_u64 v[214:215], s[22:23], 0, v[0:1]
	s_add_i32 m0, s49, 0x2000
	s_nop 0
	global_load_lds_dwordx4 v[214:215], off
	s_barrier
	s_waitcnt lgkmcnt(0)
	s_waitcnt lgkmcnt(0)
	v_mfma_f32_16x16x32_bf16 v[84:87], v[204:207], v[172:175], 0
	v_mfma_f32_16x16x32_bf16 v[76:79], v[220:223], v[172:175], 0
	v_mfma_f32_16x16x32_bf16 v[72:75], v[204:207], v[180:183], 0
	v_mfma_f32_16x16x32_bf16 v[68:71], v[220:223], v[180:183], 0
	v_mfma_f32_16x16x32_bf16 v[56:59], v[204:207], v[188:191], 0
	v_mfma_f32_16x16x32_bf16 v[52:55], v[220:223], v[188:191], 0
	v_mfma_f32_16x16x32_bf16 v[44:47], v[204:207], v[196:199], 0
	v_mfma_f32_16x16x32_bf16 v[36:39], v[220:223], v[196:199], 0
	v_mfma_f32_16x16x32_bf16 v[84:87], v[208:211], v[176:179], v[84:87]
	v_mfma_f32_16x16x32_bf16 v[76:79], v[234:237], v[176:179], v[76:79]
	v_mfma_f32_16x16x32_bf16 v[72:75], v[208:211], v[184:187], v[72:75]
	v_mfma_f32_16x16x32_bf16 v[68:71], v[234:237], v[184:187], v[68:71]
	v_mfma_f32_16x16x32_bf16 v[56:59], v[208:211], v[192:195], v[56:59]
	v_mfma_f32_16x16x32_bf16 v[52:55], v[234:237], v[192:195], v[52:55]
	v_mfma_f32_16x16x32_bf16 v[44:47], v[208:211], v[200:203], v[44:47]
	v_mfma_f32_16x16x32_bf16 v[36:39], v[234:237], v[200:203], v[36:39]
	s_mov_b32 m0, s30
	v_lshl_add_u64 v[224:225], s[16:17], 0, v[134:135]
	s_barrier
	ds_read_b128 v[172:175], v146 offset:16384
	ds_read_b128 v[176:179], v146 offset:17408
	ds_read_b128 v[180:183], v146 offset:18432
	ds_read_b128 v[184:187], v146 offset:19456
	ds_read_b128 v[188:191], v146 offset:20480
	ds_read_b128 v[192:195], v146 offset:21504
	ds_read_b128 v[196:199], v146 offset:22528
	ds_read_b128 v[200:203], v146 offset:23552
	global_load_lds_dwordx4 v[224:225], off
	v_lshl_add_u64 v[238:239], s[16:17], 0, v[132:133]
	s_mov_b32 m0, s31
	s_nop 0
	global_load_lds_dwordx4 v[238:239], off
	s_barrier
	s_waitcnt lgkmcnt(0)
	s_waitcnt lgkmcnt(0)
	v_mfma_f32_16x16x32_bf16 v[96:99], v[148:151], v[172:175], 0
	v_mfma_f32_16x16x32_bf16 v[92:95], v[156:159], v[172:175], 0
	v_mfma_f32_16x16x32_bf16 v[88:91], v[148:151], v[180:183], 0
	v_mfma_f32_16x16x32_bf16 v[80:83], v[156:159], v[180:183], 0
	v_mfma_f32_16x16x32_bf16 v[64:67], v[148:151], v[188:191], 0
	v_mfma_f32_16x16x32_bf16 v[60:63], v[156:159], v[188:191], 0
	v_mfma_f32_16x16x32_bf16 v[48:51], v[148:151], v[196:199], 0
	v_mfma_f32_16x16x32_bf16 v[40:43], v[156:159], v[196:199], 0
	v_mfma_f32_16x16x32_bf16 v[96:99], v[152:155], v[176:179], v[96:99]
	v_mfma_f32_16x16x32_bf16 v[92:95], v[160:163], v[176:179], v[92:95]
	v_mfma_f32_16x16x32_bf16 v[88:91], v[152:155], v[184:187], v[88:91]
	v_mfma_f32_16x16x32_bf16 v[80:83], v[160:163], v[184:187], v[80:83]
	v_mfma_f32_16x16x32_bf16 v[64:67], v[152:155], v[192:195], v[64:67]
	v_mfma_f32_16x16x32_bf16 v[60:63], v[160:163], v[192:195], v[60:63]
	v_mfma_f32_16x16x32_bf16 v[48:51], v[152:155], v[200:203], v[48:51]
	v_mfma_f32_16x16x32_bf16 v[40:43], v[160:163], v[200:203], v[40:43]
	s_barrier
	s_add_u32 s74, s22, 0x100000
	s_addc_u32 s75, s23, 0
	s_add_i32 s49, s73, s27
	v_lshl_add_u64 v[148:149], s[74:75], 0, v[2:3]
	s_mov_b32 m0, s49
	s_nop 0
	global_load_lds_dwordx4 v[148:149], off
	v_lshl_add_u64 v[148:149], s[74:75], 0, v[0:1]
	s_add_i32 m0, s49, 0x2000
	s_nop 0
	global_load_lds_dwordx4 v[148:149], off
	s_waitcnt vmcnt(6)
	s_barrier
	v_mfma_f32_16x16x32_bf16 v[32:35], v[204:207], v[172:175], 0
	v_mfma_f32_16x16x32_bf16 v[28:31], v[220:223], v[172:175], 0
	v_mfma_f32_16x16x32_bf16 v[24:27], v[204:207], v[180:183], 0
	v_mfma_f32_16x16x32_bf16 v[20:23], v[220:223], v[180:183], 0
	v_mfma_f32_16x16x32_bf16 v[16:19], v[204:207], v[188:191], 0
	v_mfma_f32_16x16x32_bf16 v[12:15], v[220:223], v[188:191], 0
	v_mfma_f32_16x16x32_bf16 v[8:11], v[204:207], v[196:199], 0
	v_mfma_f32_16x16x32_bf16 v[4:7], v[220:223], v[196:199], 0
	v_mfma_f32_16x16x32_bf16 v[32:35], v[208:211], v[176:179], v[32:35]
	v_mfma_f32_16x16x32_bf16 v[28:31], v[234:237], v[176:179], v[28:31]
	v_mfma_f32_16x16x32_bf16 v[24:27], v[208:211], v[184:187], v[24:27]
	v_mfma_f32_16x16x32_bf16 v[20:23], v[234:237], v[184:187], v[20:23]
	v_mfma_f32_16x16x32_bf16 v[16:19], v[208:211], v[192:195], v[16:19]
	v_mfma_f32_16x16x32_bf16 v[12:15], v[234:237], v[192:195], v[12:15]
	v_mfma_f32_16x16x32_bf16 v[8:11], v[208:211], v[200:203], v[8:11]
	v_mfma_f32_16x16x32_bf16 v[4:7], v[234:237], v[200:203], v[4:7]
	s_add_i32 s49, 0, 0x18000
	v_add_u32_e32 v147, s49, v141
	s_barrier
	ds_read_b128 v[148:151], v147
	ds_read_b128 v[152:155], v147 offset:1024
	ds_read_b128 v[156:159], v147 offset:2048
	ds_read_b128 v[160:163], v147 offset:3072
	s_add_u32 s16, s16, 0x100000
	s_addc_u32 s17, s17, 0
	s_mov_b32 m0, s36
	v_lshl_add_u64 v[204:205], s[16:17], 0, v[134:135]
	ds_read_b128 v[172:175], v146 offset:32768
	ds_read_b128 v[176:179], v146 offset:33792
	ds_read_b128 v[180:183], v146 offset:34816
	ds_read_b128 v[184:187], v146 offset:35840
	ds_read_b128 v[188:191], v146 offset:36864
	ds_read_b128 v[192:195], v146 offset:37888
	ds_read_b128 v[196:199], v146 offset:38912
	ds_read_b128 v[200:203], v146 offset:39936
	global_load_lds_dwordx4 v[204:205], off
	v_lshl_add_u64 v[204:205], s[16:17], 0, v[132:133]
	s_mov_b32 m0, s37
	s_nop 0
	global_load_lds_dwordx4 v[204:205], off
	s_waitcnt lgkmcnt(8)
	s_barrier
	s_waitcnt lgkmcnt(0)
	s_waitcnt lgkmcnt(0)
	v_mfma_f32_16x16x32_bf16 v[128:131], v[148:151], v[172:175], v[128:131]
	v_mfma_f32_16x16x32_bf16 v[124:127], v[156:159], v[172:175], v[124:127]
	v_mfma_f32_16x16x32_bf16 v[120:123], v[148:151], v[180:183], v[120:123]
	v_mfma_f32_16x16x32_bf16 v[116:119], v[156:159], v[180:183], v[116:119]
	v_mfma_f32_16x16x32_bf16 v[112:115], v[148:151], v[188:191], v[112:115]
	v_mfma_f32_16x16x32_bf16 v[108:111], v[156:159], v[188:191], v[108:111]
	v_mfma_f32_16x16x32_bf16 v[104:107], v[148:151], v[196:199], v[104:107]
	v_mfma_f32_16x16x32_bf16 v[100:103], v[156:159], v[196:199], v[100:103]
	v_mfma_f32_16x16x32_bf16 v[128:131], v[152:155], v[176:179], v[128:131]
	v_mfma_f32_16x16x32_bf16 v[124:127], v[160:163], v[176:179], v[124:127]
	v_mfma_f32_16x16x32_bf16 v[120:123], v[152:155], v[184:187], v[120:123]
	v_mfma_f32_16x16x32_bf16 v[116:119], v[160:163], v[184:187], v[116:119]
	v_mfma_f32_16x16x32_bf16 v[112:115], v[152:155], v[192:195], v[112:115]
	v_mfma_f32_16x16x32_bf16 v[108:111], v[160:163], v[192:195], v[108:111]
	v_mfma_f32_16x16x32_bf16 v[104:107], v[152:155], v[200:203], v[104:107]
	v_mfma_f32_16x16x32_bf16 v[100:103], v[160:163], v[200:203], v[100:103]
	s_barrier
	s_add_i32 s73, 0, 0x1c000
	s_add_i32 s16, s49, s27
	v_add_u32_e32 v147, s73, v141
	v_lshl_add_u64 v[168:169], v[168:169], 0, s[28:29]
	s_mov_b32 m0, s16
	ds_read_b128 v[204:207], v147
	ds_read_b128 v[208:211], v147 offset:1024
	ds_read_b128 v[220:223], v147 offset:2048
	ds_read_b128 v[234:237], v147 offset:3072
	global_load_lds_dwordx4 v[168:169], off
	v_lshl_add_u64 v[168:169], v[214:215], 0, s[28:29]
	s_add_i32 m0, s16, 0x2000
	s_nop 0
	global_load_lds_dwordx4 v[168:169], off
	s_barrier
	s_waitcnt lgkmcnt(0)
	s_waitcnt lgkmcnt(0)
	v_mfma_f32_16x16x32_bf16 v[84:87], v[204:207], v[172:175], v[84:87]
	v_mfma_f32_16x16x32_bf16 v[76:79], v[220:223], v[172:175], v[76:79]
	v_mfma_f32_16x16x32_bf16 v[72:75], v[204:207], v[180:183], v[72:75]
	v_mfma_f32_16x16x32_bf16 v[68:71], v[220:223], v[180:183], v[68:71]
	v_mfma_f32_16x16x32_bf16 v[56:59], v[204:207], v[188:191], v[56:59]
	v_mfma_f32_16x16x32_bf16 v[52:55], v[220:223], v[188:191], v[52:55]
	v_mfma_f32_16x16x32_bf16 v[44:47], v[204:207], v[196:199], v[44:47]
	v_mfma_f32_16x16x32_bf16 v[36:39], v[220:223], v[196:199], v[36:39]
	v_mfma_f32_16x16x32_bf16 v[84:87], v[208:211], v[176:179], v[84:87]
	v_mfma_f32_16x16x32_bf16 v[76:79], v[234:237], v[176:179], v[76:79]
	v_mfma_f32_16x16x32_bf16 v[72:75], v[208:211], v[184:187], v[72:75]
	v_mfma_f32_16x16x32_bf16 v[68:71], v[234:237], v[184:187], v[68:71]
	v_mfma_f32_16x16x32_bf16 v[56:59], v[208:211], v[192:195], v[56:59]
	v_mfma_f32_16x16x32_bf16 v[52:55], v[234:237], v[192:195], v[52:55]
	v_mfma_f32_16x16x32_bf16 v[44:47], v[208:211], v[200:203], v[44:47]
	v_mfma_f32_16x16x32_bf16 v[36:39], v[234:237], v[200:203], v[36:39]
	s_mov_b32 m0, s50
	v_lshl_add_u64 v[168:169], v[224:225], 0, s[28:29]
	s_barrier
	ds_read_b128 v[172:175], v146 offset:49152
	ds_read_b128 v[176:179], v146 offset:50176
	ds_read_b128 v[180:183], v146 offset:51200
	ds_read_b128 v[184:187], v146 offset:52224
	ds_read_b128 v[188:191], v146 offset:53248
	ds_read_b128 v[192:195], v146 offset:54272
	ds_read_b128 v[196:199], v146 offset:55296
	ds_read_b128 v[200:203], v146 offset:56320
	global_load_lds_dwordx4 v[168:169], off
	v_lshl_add_u64 v[168:169], v[238:239], 0, s[28:29]
	s_mov_b32 m0, s51
	s_nop 0
	global_load_lds_dwordx4 v[168:169], off
	s_barrier
	s_waitcnt lgkmcnt(0)
	s_waitcnt lgkmcnt(0)
	v_mfma_f32_16x16x32_bf16 v[96:99], v[148:151], v[172:175], v[96:99]
	v_mfma_f32_16x16x32_bf16 v[92:95], v[156:159], v[172:175], v[92:95]
	v_mfma_f32_16x16x32_bf16 v[88:91], v[148:151], v[180:183], v[88:91]
	v_mfma_f32_16x16x32_bf16 v[80:83], v[156:159], v[180:183], v[80:83]
	v_mfma_f32_16x16x32_bf16 v[64:67], v[148:151], v[188:191], v[64:67]
	v_mfma_f32_16x16x32_bf16 v[60:63], v[156:159], v[188:191], v[60:63]
	v_mfma_f32_16x16x32_bf16 v[48:51], v[148:151], v[196:199], v[48:51]
	v_mfma_f32_16x16x32_bf16 v[40:43], v[156:159], v[196:199], v[40:43]
	v_mfma_f32_16x16x32_bf16 v[96:99], v[152:155], v[176:179], v[96:99]
	v_mfma_f32_16x16x32_bf16 v[92:95], v[160:163], v[176:179], v[92:95]
	v_mfma_f32_16x16x32_bf16 v[88:91], v[152:155], v[184:187], v[88:91]
	v_mfma_f32_16x16x32_bf16 v[80:83], v[160:163], v[184:187], v[80:83]
	v_mfma_f32_16x16x32_bf16 v[64:67], v[152:155], v[192:195], v[64:67]
	v_mfma_f32_16x16x32_bf16 v[60:63], v[160:163], v[192:195], v[60:63]
	v_mfma_f32_16x16x32_bf16 v[48:51], v[152:155], v[200:203], v[48:51]
	v_mfma_f32_16x16x32_bf16 v[40:43], v[160:163], v[200:203], v[40:43]
	s_barrier
	s_add_u32 s16, s22, 0x100080
	s_addc_u32 s17, s23, 0
	s_add_i32 s22, s73, s27
	v_lshl_add_u64 v[148:149], s[16:17], 0, v[2:3]
	s_mov_b32 m0, s22
	s_nop 0
	global_load_lds_dwordx4 v[148:149], off
	v_lshl_add_u64 v[148:149], s[16:17], 0, v[0:1]
	s_add_i32 m0, s22, 0x2000
	s_nop 0
	global_load_lds_dwordx4 v[148:149], off
	s_waitcnt vmcnt(6)
	s_barrier
	v_mfma_f32_16x16x32_bf16 v[32:35], v[204:207], v[172:175], v[32:35]
	v_mfma_f32_16x16x32_bf16 v[28:31], v[220:223], v[172:175], v[28:31]
	v_mfma_f32_16x16x32_bf16 v[24:27], v[204:207], v[180:183], v[24:27]
	v_mfma_f32_16x16x32_bf16 v[20:23], v[220:223], v[180:183], v[20:23]
	v_mfma_f32_16x16x32_bf16 v[16:19], v[204:207], v[188:191], v[16:19]
	v_mfma_f32_16x16x32_bf16 v[12:15], v[220:223], v[188:191], v[12:15]
	v_mfma_f32_16x16x32_bf16 v[8:11], v[204:207], v[196:199], v[8:11]
	v_mfma_f32_16x16x32_bf16 v[4:7], v[220:223], v[196:199], v[4:7]
	v_mfma_f32_16x16x32_bf16 v[32:35], v[208:211], v[176:179], v[32:35]
	v_mfma_f32_16x16x32_bf16 v[28:31], v[234:237], v[176:179], v[28:31]
	v_mfma_f32_16x16x32_bf16 v[24:27], v[208:211], v[184:187], v[24:27]
	v_mfma_f32_16x16x32_bf16 v[20:23], v[234:237], v[184:187], v[20:23]
	v_mfma_f32_16x16x32_bf16 v[16:19], v[208:211], v[192:195], v[16:19]
	v_mfma_f32_16x16x32_bf16 v[12:15], v[234:237], v[192:195], v[12:15]
	v_mfma_f32_16x16x32_bf16 v[8:11], v[208:211], v[200:203], v[8:11]
	v_mfma_f32_16x16x32_bf16 v[4:7], v[234:237], v[200:203], v[4:7]
	s_add_i32 s48, s48, 2
	s_add_u32 s20, s20, 0x100
	s_addc_u32 s21, s21, 0
	s_add_u32 s3, s3, 0x100
	s_addc_u32 s5, s5, 0
	s_cmp_gt_u32 s48, 61
	s_barrier
